# even in-projection GEMM K-loop switched to the simple LDS-DMA structure (2 stages, 1 barrier/step, burst reads); rest as previous
# speedup vs baseline: 1.0096x; 1.0022x over previous
; DI int tid_l() { int t = threadIdx.x; asm volatile("" : "+v"(t)); return t; }
; DI int bid_l() { int t = blockIdx.x; asm volatile("" : "+s"(t)); return t; }
; DI f32x16 zero16() { f32x16 z; for (int i = 0; i < 16; ++i) z[i] = 0.f; return z; }
; template <int MF, int BK, class Epi>
; DI void gemm_phase_t(char* lds, const GemmDesc g, const Epi epi) {
;   constexpr int BM = MF * 64, LS = BK + 8, CPR = BK / 8, RSTEP = 256 / CPR;
;   constexpr int APT = BM * CPR / 256, BPT = 128 * CPR / 256, STG = (BM + 128) * LS, NKK = BK / 16;
;   u16* sbase = (u16*)lds;
;   const int tid = tid_l(), lane = tid & 63, w = tid >> 6, wm = w >> 1, wn = w & 1, l31 = lane & 31, h = lane >> 5;
;   const int ntn = g.Npad / 128, ntm = g.M / BM, ntiles = ntm * ntn, nk = g.K / BK;
;   const int lr = tid / CPR, lc = tid % CPR;
;   for (int t = bid_l(); t < ntiles; t += gridDim.x) {
;     const int tn = t % ntn, tm = t / ntn;
;     const int m0 = tm * BM, n0 = tn * 128;
;     const u16* Ap = g.A + (size_t)(m0 + lr) * g.lda + lc * 8;
;     const u16* Bp = g.Bt + (size_t)(n0 + lr) * g.ldb + lc * 8;
;     u32x4 ra[APT], rb[BPT];
; #pragma unroll
;     for (int j = 0; j < APT; ++j) ra[j] = *(const u32x4*)(Ap + (size_t)j * RSTEP * g.lda);
; #pragma unroll
;     for (int j = 0; j < BPT; ++j) rb[j] = *(const u32x4*)(Bp + (size_t)j * RSTEP * g.ldb);
; #pragma unroll
;     for (int j = 0; j < APT; ++j) *(u32x4*)(sbase + (lr + RSTEP * j) * LS + lc * 8) = ra[j];
; #pragma unroll
;     for (int j = 0; j < BPT; ++j) *(u32x4*)(sbase + BM * LS + (lr + RSTEP * j) * LS + lc * 8) = rb[j];
;     if (nk > 1) {
; #pragma unroll
;       for (int j = 0; j < APT; ++j) ra[j] = *(const u32x4*)(Ap + (size_t)j * RSTEP * g.lda + BK);
; #pragma unroll
;       for (int j = 0; j < BPT; ++j) rb[j] = *(const u32x4*)(Bp + (size_t)j * RSTEP * g.ldb + BK);
;     }
;     f32x16 acc[MF][2];
; #pragma unroll
;     for (int i = 0; i < MF; ++i)
; #pragma unroll
;       for (int j = 0; j < 2; ++j) acc[i][j] = zero16();
.LBB0_950:
	s_and_b64 vcc, exec, s[0:1]
	s_cbranch_vccz .LBB0_957
	v_mov_b32_e32 v4, v0
	v_readlane_b32 s10, v251, 0
	v_mov_b32_e32 v203, 0x42800000
	v_mov_b32_e32 v208, 0x13004
	v_mov_b32_e32 v214, 0x13000
	s_cmpk_gt_i32 s10, 0x10ff
	s_cbranch_scc1 .LBB0_956
	v_ashrrev_i32_e32 v2, 31, v4
	v_lshrrev_b32_e32 v2, 30, v2
	v_add_u32_e32 v5, v4, v2
	v_ashrrev_i32_e32 v2, 2, v5
	v_and_b32_e32 v5, -4, v5
	v_sub_u32_e32 v5, v4, v5
	v_lshlrev_b32_e32 v6, 3, v5
	v_ashrrev_i32_e32 v7, 31, v6
	s_waitcnt vmcnt(10)
	v_lshl_add_u64 v[156:157], v[6:7], 1, s[30:31]
	s_mov_b64 s[0:1], 0x147ac000
	s_add_u32 s6, s30, 0x37ac000
	s_waitcnt vmcnt(9)
	v_lshl_add_u64 v[158:159], v[156:157], 0, s[0:1]
	s_mov_b64 s[0:1], 0xc4c000
	s_addc_u32 s7, s31, 0
	v_bfe_u32 v8, v4, 5, 1
	v_and_b32_e32 v9, 64, v4
	v_lshl_add_u64 v[160:161], v[156:157], 0, s[0:1]
	v_and_b32_e32 v6, 0x5f, v4
	v_and_b32_e32 v168, 0xffffff9f, v4
	v_or_b32_e32 v4, 0x60, v4
	s_movk_i32 s0, 0x50
	s_add_u32 s8, s30, 0xe1ac000
	v_lshlrev_b32_e32 v5, 4, v5
	v_lshlrev_b32_e32 v7, 4, v8
	v_lshl_or_b32 v169, v8, 3, v9
	v_mul_lo_u32 v4, v4, s0
	v_mul_lo_u32 v8, v2, s0
	v_mul_lo_u32 v9, v168, s0
	v_mul_u32_u24_e32 v6, 0x50, v6
	s_addc_u32 s9, s31, 0
	v_bfe_u32 v4, v0, 2, 2
	v_bfe_u32 v5, v0, 5, 1
	v_xor_b32_e32 v4, v4, v5
	v_lshlrev_b32_e32 v4, 4, v4
	v_add_u32_e32 v4, 0x100, v4
	v_and_b32_e32 v5, 31, v0
	v_bfe_u32 v6, v0, 7, 1
	v_lshl_or_b32 v6, v6, 7, v5
	v_lshl_add_u32 v172, v6, 6, v4
	v_bfe_u32 v6, v0, 6, 1
	v_lshl_or_b32 v6, v6, 6, v5
	v_lshl_add_u32 v171, v6, 6, v4
	v_add_u32_e32 v171, 0x4000, v171
	v_xor_b32_e32 v173, 0x20, v172
	v_xor_b32_e32 v170, 0x20, v171
.LBB0_953:
	s_ashr_i32 s0, s10, 31
	s_lshr_b32 s0, s0, 27
	s_add_i32 s0, s10, s0
	s_and_b32 s1, s0, 0x1ffffe0
	s_lshl_b32 s0, s0, 3
	s_and_b32 s2, s0, 0xffffff00
	v_add_u32_e32 v4, s2, v2
	v_ashrrev_i32_e32 v5, 31, v4
	s_sub_i32 s1, s10, s1
	v_lshlrev_b64 v[68:69], 11, v[4:5]
	s_lshl_b32 s3, s1, 7
	v_lshl_add_u64 v[70:71], v[158:159], 0, v[68:69]
	v_add_u32_e32 v4, s3, v2
	v_ashrrev_i32_e32 v5, 31, v4
	v_lshlrev_b64 v[72:73], 11, v[4:5]
	v_lshl_add_u64 v[80:81], v[160:161], 0, v[72:73]
	v_mov_b32_e32 v60, 0
	v_readfirstlane_b32 s98, v70
	v_readfirstlane_b32 s99, v71
	v_readfirstlane_b32 s100, v80
	v_readfirstlane_b32 s101, v81
	v_bfe_u32 v62, v0, 4, 2
	v_and_b32_e32 v63, 3, v0
	v_xor_b32_e32 v62, v62, v63
	v_lshlrev_b32_e32 v62, 4, v62
	v_bfe_u32 v63, v0, 2, 4
	s_movk_i32 s0, 0x800
	v_mad_u32_u24 v194, v63, s0, v62
	v_add_u32_e32 v195, 0x20000, v194
	v_add_u32_e32 v198, 0x40000, v194
	v_add_u32_e32 v199, 0x60000, v194
	v_lshrrev_b32_e32 v61, 6, v0
	v_lshlrev_b32_e32 v61, 10, v61
	v_add_u32_e32 v61, 0x100, v61
	s_nop 0
	v_readfirstlane_b32 s1, v61
	v_mov_b32_e32 v4, 0
	v_mov_b32_e32 v5, 0
	v_mov_b32_e32 v6, 0
	v_mov_b32_e32 v7, 0
	v_mov_b32_e32 v8, 0
	v_mov_b32_e32 v9, 0
	v_mov_b32_e32 v10, 0
	v_mov_b32_e32 v11, 0
	v_mov_b32_e32 v12, 0
	v_mov_b32_e32 v13, 0
	v_mov_b32_e32 v14, 0
	v_mov_b32_e32 v15, 0
	v_mov_b32_e32 v16, 0
	v_mov_b32_e32 v17, 0
	v_mov_b32_e32 v18, 0
	v_mov_b32_e32 v19, 0
	v_mov_b32_e32 v20, 0
	v_mov_b32_e32 v21, 0
	v_mov_b32_e32 v22, 0
	v_mov_b32_e32 v23, 0
	v_mov_b32_e32 v24, 0
	v_mov_b32_e32 v25, 0
	v_mov_b32_e32 v26, 0
	v_mov_b32_e32 v27, 0
	v_mov_b32_e32 v28, 0
	v_mov_b32_e32 v29, 0
	v_mov_b32_e32 v30, 0
	v_mov_b32_e32 v31, 0
	v_mov_b32_e32 v32, 0
	v_mov_b32_e32 v33, 0
	v_mov_b32_e32 v34, 0
	v_mov_b32_e32 v35, 0
	v_mov_b32_e32 v36, 0
	v_mov_b32_e32 v37, 0
	v_mov_b32_e32 v38, 0
	v_mov_b32_e32 v39, 0
	v_mov_b32_e32 v40, 0
	v_mov_b32_e32 v41, 0
	v_mov_b32_e32 v42, 0
	v_mov_b32_e32 v43, 0
	v_mov_b32_e32 v44, 0
	v_mov_b32_e32 v45, 0
	v_mov_b32_e32 v46, 0
	v_mov_b32_e32 v47, 0
	v_mov_b32_e32 v48, 0
	v_mov_b32_e32 v49, 0
	v_mov_b32_e32 v50, 0
	v_mov_b32_e32 v51, 0
	v_mov_b32_e32 v52, 0
	v_mov_b32_e32 v53, 0
	v_mov_b32_e32 v54, 0
	v_mov_b32_e32 v55, 0
	v_mov_b32_e32 v56, 0
	v_mov_b32_e32 v57, 0
	v_mov_b32_e32 v58, 0
	v_mov_b32_e32 v59, 0
	v_mov_b32_e32 v60, 0
	v_mov_b32_e32 v61, 0
	v_mov_b32_e32 v62, 0
	v_mov_b32_e32 v63, 0
	v_mov_b32_e32 v64, 0
	v_mov_b32_e32 v65, 0
	v_mov_b32_e32 v66, 0
	v_mov_b32_e32 v67, 0
	v_mov_b32_e32 v68, 0
	v_mov_b32_e32 v69, 0
	v_mov_b32_e32 v70, 0
	v_mov_b32_e32 v71, 0
	v_mov_b32_e32 v72, 0
	v_mov_b32_e32 v73, 0
	v_mov_b32_e32 v74, 0
	v_mov_b32_e32 v75, 0
	v_mov_b32_e32 v76, 0
	v_mov_b32_e32 v77, 0
	v_mov_b32_e32 v78, 0
	v_mov_b32_e32 v79, 0
	v_mov_b32_e32 v80, 0
	v_mov_b32_e32 v81, 0
	v_mov_b32_e32 v82, 0
	v_mov_b32_e32 v83, 0
	v_mov_b32_e32 v84, 0
	v_mov_b32_e32 v85, 0
	v_mov_b32_e32 v86, 0
	v_mov_b32_e32 v87, 0
	v_mov_b32_e32 v88, 0
	v_mov_b32_e32 v89, 0
	v_mov_b32_e32 v90, 0
	v_mov_b32_e32 v91, 0
	v_mov_b32_e32 v92, 0
	v_mov_b32_e32 v93, 0
	v_mov_b32_e32 v94, 0
	v_mov_b32_e32 v95, 0
	v_mov_b32_e32 v96, 0
	v_mov_b32_e32 v97, 0
	v_mov_b32_e32 v98, 0
	v_mov_b32_e32 v99, 0
	v_mov_b32_e32 v100, 0
	v_mov_b32_e32 v101, 0
	v_mov_b32_e32 v102, 0
	v_mov_b32_e32 v103, 0
	v_mov_b32_e32 v104, 0
	v_mov_b32_e32 v105, 0
	v_mov_b32_e32 v106, 0
	v_mov_b32_e32 v107, 0
	v_mov_b32_e32 v108, 0
	v_mov_b32_e32 v109, 0
	v_mov_b32_e32 v110, 0
	v_mov_b32_e32 v111, 0
	v_mov_b32_e32 v112, 0
	v_mov_b32_e32 v113, 0
	v_mov_b32_e32 v114, 0
	v_mov_b32_e32 v115, 0
	v_mov_b32_e32 v116, 0
	v_mov_b32_e32 v117, 0
	v_mov_b32_e32 v118, 0
	v_mov_b32_e32 v119, 0
	v_mov_b32_e32 v120, 0
	v_mov_b32_e32 v121, 0
	v_mov_b32_e32 v122, 0
	v_mov_b32_e32 v123, 0
	v_mov_b32_e32 v124, 0
	v_mov_b32_e32 v125, 0
	v_mov_b32_e32 v126, 0
	v_mov_b32_e32 v127, 0
	v_mov_b32_e32 v128, 0
	v_mov_b32_e32 v129, 0
	v_mov_b32_e32 v130, 0
	v_mov_b32_e32 v131, 0
	s_add_i32 m0, s1, 0x0
	s_nop 0
	global_load_lds_dwordx4 v194, s[98:99]
	s_add_i32 m0, s1, 0x1000
	s_nop 0
	global_load_lds_dwordx4 v195, s[98:99]
	s_add_i32 m0, s1, 0x2000
	s_nop 0
	global_load_lds_dwordx4 v198, s[98:99]
	s_add_i32 m0, s1, 0x3000
	s_nop 0
	global_load_lds_dwordx4 v199, s[98:99]
	s_add_i32 m0, s1, 0x4000
	s_nop 0
	global_load_lds_dwordx4 v194, s[100:101]
	s_add_i32 m0, s1, 0x5000
	s_nop 0
	global_load_lds_dwordx4 v195, s[100:101]
	s_add_u32 s98, s98, 0x40
	s_addc_u32 s99, s99, 0
	s_add_u32 s100, s100, 0x40
	s_addc_u32 s101, s101, 0
	s_movk_i32 s0, 15
; #define MFMA32(a, b, c) __builtin_amdgcn_mfma_f32_32x32x16_bf16((a), (b), (c), 0, 0, 0)
; template <int MF, int BK, class Epi>
; DI void gemm_phase_t(char* lds, const GemmDesc g, const Epi epi) {
;     ...
;     for (int kt = 0; kt < nk; ++kt) {
;       __syncthreads();
;       const u16* sA = sbase + (kt & 1) * STG;
;       const u16* sB = sA + BM * LS;
;       if (kt + 1 < nk) {
;         u16* nA = sbase + ((kt + 1) & 1) * STG;
; #pragma unroll
;         for (int j = 0; j < APT; ++j) *(u32x4*)(nA + (lr + RSTEP * j) * LS + lc * 8) = ra[j];
; #pragma unroll
;         for (int j = 0; j < BPT; ++j) *(u32x4*)(nA + BM * LS + (lr + RSTEP * j) * LS + lc * 8) = rb[j];
;         if (kt + 2 < nk) {
; #pragma unroll
;           for (int j = 0; j < APT; ++j) ra[j] = *(const u32x4*)(Ap + (size_t)j * RSTEP * g.lda + (kt + 2) * BK);
; #pragma unroll
;           for (int j = 0; j < BPT; ++j) rb[j] = *(const u32x4*)(Bp + (size_t)j * RSTEP * g.ldb + (kt + 2) * BK);
;         }
;       }
;       bf16x8 af[NKK][MF], bfr[NKK][2];
; #pragma unroll
;       for (int kk = 0; kk < NKK; ++kk) {
; #pragma unroll
;         for (int ni = 0; ni < 2; ++ni) bfr[kk][ni] = *(const bf16x8*)(sB + (wn * 64 + ni * 32 + l31) * LS + kk * 16 + h * 8);
; #pragma unroll
;         for (int mi = 0; mi < MF; ++mi) af[kk][mi] = *(const bf16x8*)(sA + (wm * (MF * 32) + mi * 32 + l31) * LS + kk * 16 + h * 8);
;       }
;       __builtin_amdgcn_sched_barrier(0);
; #pragma unroll
;       for (int kk = 0; kk < NKK; ++kk)
; #pragma unroll
;         for (int mi = 0; mi < MF; ++mi)
; #pragma unroll
;           for (int ni = 0; ni < 2; ++ni) acc[mi][ni] = MFMA32(bfr[kk][ni], af[kk][mi], acc[mi][ni]);
.Ldma_ie_loop:
	s_waitcnt vmcnt(0)
	s_waitcnt lgkmcnt(0)
	s_barrier
	s_add_i32 m0, s1, 0x6000
	s_nop 0
	global_load_lds_dwordx4 v194, s[98:99]
	s_add_i32 m0, s1, 0x7000
	s_nop 0
	global_load_lds_dwordx4 v195, s[98:99]
	s_add_i32 m0, s1, 0x8000
	s_nop 0
	global_load_lds_dwordx4 v198, s[98:99]
	s_add_i32 m0, s1, 0x9000
	s_nop 0
	global_load_lds_dwordx4 v199, s[98:99]
	s_add_i32 m0, s1, 0xa000
	s_nop 0
	global_load_lds_dwordx4 v194, s[100:101]
	s_add_i32 m0, s1, 0xb000
	s_nop 0
	global_load_lds_dwordx4 v195, s[100:101]
	s_add_u32 s98, s98, 0x40
	s_addc_u32 s99, s99, 0
	s_add_u32 s100, s100, 0x40
	s_addc_u32 s101, s101, 0
	ds_read_b128 v[132:135], v171
	ds_read_b128 v[136:139], v171 offset:2048
	ds_read_b128 v[140:143], v172
	ds_read_b128 v[144:147], v172 offset:2048
	ds_read_b128 v[148:151], v172 offset:4096
	ds_read_b128 v[152:155], v172 offset:6144
	ds_read_b128 v[174:177], v170
	ds_read_b128 v[178:181], v170 offset:2048
	ds_read_b128 v[182:185], v173
	ds_read_b128 v[186:189], v173 offset:2048
	ds_read_b128 v[190:193], v173 offset:4096
	ds_read_b128 v[218:221], v173 offset:6144
	s_waitcnt lgkmcnt(0)
	v_mfma_f32_32x32x16_bf16 v[116:131], v[132:135], v[140:143], v[116:131]
	v_mfma_f32_32x32x16_bf16 v[100:115], v[136:139], v[140:143], v[100:115]
	v_mfma_f32_32x32x16_bf16 v[84:99], v[132:135], v[144:147], v[84:99]
	v_mfma_f32_32x32x16_bf16 v[68:83], v[136:139], v[144:147], v[68:83]
	v_mfma_f32_32x32x16_bf16 v[52:67], v[132:135], v[148:151], v[52:67]
	v_mfma_f32_32x32x16_bf16 v[36:51], v[136:139], v[148:151], v[36:51]
	v_mfma_f32_32x32x16_bf16 v[20:35], v[132:135], v[152:155], v[20:35]
	v_mfma_f32_32x32x16_bf16 v[4:19], v[136:139], v[152:155], v[4:19]
	v_mfma_f32_32x32x16_bf16 v[116:131], v[174:177], v[182:185], v[116:131]
	v_mfma_f32_32x32x16_bf16 v[100:115], v[178:181], v[182:185], v[100:115]
	v_mfma_f32_32x32x16_bf16 v[84:99], v[174:177], v[186:189], v[84:99]
	v_mfma_f32_32x32x16_bf16 v[68:83], v[178:181], v[186:189], v[68:83]
	v_mfma_f32_32x32x16_bf16 v[52:67], v[174:177], v[190:193], v[52:67]
	v_mfma_f32_32x32x16_bf16 v[36:51], v[178:181], v[190:193], v[36:51]
	v_mfma_f32_32x32x16_bf16 v[20:35], v[174:177], v[218:221], v[20:35]
	v_mfma_f32_32x32x16_bf16 v[4:19], v[178:181], v[218:221], v[4:19]
	s_waitcnt vmcnt(0)
	s_waitcnt lgkmcnt(0)
	s_barrier
	s_add_i32 m0, s1, 0x0
	s_nop 0
	global_load_lds_dwordx4 v194, s[98:99]
	s_add_i32 m0, s1, 0x1000
	s_nop 0
	global_load_lds_dwordx4 v195, s[98:99]
	s_add_i32 m0, s1, 0x2000
	s_nop 0
	global_load_lds_dwordx4 v198, s[98:99]
	s_add_i32 m0, s1, 0x3000
	s_nop 0
	global_load_lds_dwordx4 v199, s[98:99]
	s_add_i32 m0, s1, 0x4000
	s_nop 0
	global_load_lds_dwordx4 v194, s[100:101]
	s_add_i32 m0, s1, 0x5000
	s_nop 0
	global_load_lds_dwordx4 v195, s[100:101]
	s_add_u32 s98, s98, 0x40
	s_addc_u32 s99, s99, 0
	s_add_u32 s100, s100, 0x40
	s_addc_u32 s101, s101, 0
	ds_read_b128 v[132:135], v171 offset:24576
	ds_read_b128 v[136:139], v171 offset:26624
	ds_read_b128 v[140:143], v172 offset:24576
	ds_read_b128 v[144:147], v172 offset:26624
	ds_read_b128 v[148:151], v172 offset:28672
	ds_read_b128 v[152:155], v172 offset:30720
	ds_read_b128 v[174:177], v170 offset:24576
	ds_read_b128 v[178:181], v170 offset:26624
	ds_read_b128 v[182:185], v173 offset:24576
	ds_read_b128 v[186:189], v173 offset:26624
	ds_read_b128 v[190:193], v173 offset:28672
	ds_read_b128 v[218:221], v173 offset:30720
	s_waitcnt lgkmcnt(0)
	v_mfma_f32_32x32x16_bf16 v[116:131], v[132:135], v[140:143], v[116:131]
	v_mfma_f32_32x32x16_bf16 v[100:115], v[136:139], v[140:143], v[100:115]
	v_mfma_f32_32x32x16_bf16 v[84:99], v[132:135], v[144:147], v[84:99]
	v_mfma_f32_32x32x16_bf16 v[68:83], v[136:139], v[144:147], v[68:83]
	v_mfma_f32_32x32x16_bf16 v[52:67], v[132:135], v[148:151], v[52:67]
	v_mfma_f32_32x32x16_bf16 v[36:51], v[136:139], v[148:151], v[36:51]
	v_mfma_f32_32x32x16_bf16 v[20:35], v[132:135], v[152:155], v[20:35]
	v_mfma_f32_32x32x16_bf16 v[4:19], v[136:139], v[152:155], v[4:19]
	v_mfma_f32_32x32x16_bf16 v[116:131], v[174:177], v[182:185], v[116:131]
	v_mfma_f32_32x32x16_bf16 v[100:115], v[178:181], v[182:185], v[100:115]
	v_mfma_f32_32x32x16_bf16 v[84:99], v[174:177], v[186:189], v[84:99]
	v_mfma_f32_32x32x16_bf16 v[68:83], v[178:181], v[186:189], v[68:83]
	v_mfma_f32_32x32x16_bf16 v[52:67], v[174:177], v[190:193], v[52:67]
	v_mfma_f32_32x32x16_bf16 v[36:51], v[178:181], v[190:193], v[36:51]
	v_mfma_f32_32x32x16_bf16 v[20:35], v[174:177], v[218:221], v[20:35]
	v_mfma_f32_32x32x16_bf16 v[4:19], v[178:181], v[218:221], v[4:19]
	s_add_i32 s0, s0, -1
	s_cmp_lg_u32 s0, 0
	s_cbranch_scc1 .Ldma_ie_loop
	s_waitcnt vmcnt(0)
	s_waitcnt lgkmcnt(0)
	s_barrier
; #define MFMA32(a, b, c) __builtin_amdgcn_mfma_f32_32x32x16_bf16((a), (b), (c), 0, 0, 0)
; template <int MF, int BK, class Epi>
; DI void gemm_phase_t(char* lds, const GemmDesc g, const Epi epi) {
;     ...
;     for (int kt = 0; kt < nk; ++kt) {
;       __syncthreads();
;       const u16* sA = sbase + (kt & 1) * STG;
;       const u16* sB = sA + BM * LS;
;       if (kt + 1 < nk) {
;         u16* nA = sbase + ((kt + 1) & 1) * STG;
; #pragma unroll
;         for (int j = 0; j < APT; ++j) *(u32x4*)(nA + (lr + RSTEP * j) * LS + lc * 8) = ra[j];
; #pragma unroll
;         for (int j = 0; j < BPT; ++j) *(u32x4*)(nA + BM * LS + (lr + RSTEP * j) * LS + lc * 8) = rb[j];
;         if (kt + 2 < nk) {
; #pragma unroll
;           for (int j = 0; j < APT; ++j) ra[j] = *(const u32x4*)(Ap + (size_t)j * RSTEP * g.lda + (kt + 2) * BK);
; #pragma unroll
;           for (int j = 0; j < BPT; ++j) rb[j] = *(const u32x4*)(Bp + (size_t)j * RSTEP * g.ldb + (kt + 2) * BK);
;         }
;       }
;       bf16x8 af[NKK][MF], bfr[NKK][2];
; #pragma unroll
;       for (int kk = 0; kk < NKK; ++kk) {
; #pragma unroll
;         for (int ni = 0; ni < 2; ++ni) bfr[kk][ni] = *(const bf16x8*)(sB + (wn * 64 + ni * 32 + l31) * LS + kk * 16 + h * 8);
; #pragma unroll
;         for (int mi = 0; mi < MF; ++mi) af[kk][mi] = *(const bf16x8*)(sA + (wm * (MF * 32) + mi * 32 + l31) * LS + kk * 16 + h * 8);
;       }
;       __builtin_amdgcn_sched_barrier(0);
; #pragma unroll
;       for (int kk = 0; kk < NKK; ++kk)
; #pragma unroll
;         for (int mi = 0; mi < MF; ++mi)
; #pragma unroll
;           for (int ni = 0; ni < 2; ++ni) acc[mi][ni] = MFMA32(bfr[kk][ni], af[kk][mi], acc[mi][ni]);
;   template <int MF> DI void operator()(f32x16 (&acc)[MF][2], int mb, int nb, int l31, int h) const {
; #pragma unroll
;     for (int mi = 0; mi < MF; ++mi) {
;       const int row = mb + mi * 32 + l31;
; #pragma unroll
;       for (int g4 = 0; g4 < 4; ++g4) {
;         const int col0 = nb + 16 * g4 + 8 * h;
;         u16* dst = (col0 < 2560) ? zhg + (size_t)row * 2560 + col0 : zhy + (size_t)row * 1536 + (col0 - 2560);
;         *(u32x4*)dst = (u32x4){pack2(acc[mi][0][4 * g4], acc[mi][0][4 * g4 + 1]), pack2(acc[mi][0][4 * g4 + 2], acc[mi][0][4 * g4 + 3]),
;                                pack2(acc[mi][1][4 * g4], acc[mi][1][4 * g4 + 1]), pack2(acc[mi][1][4 * g4 + 2], acc[mi][1][4 * g4 + 3])};
	s_add_i32 m0, s1, 0x6000
	s_nop 0
	global_load_lds_dwordx4 v194, s[98:99]
	s_add_i32 m0, s1, 0x7000
	s_nop 0
	global_load_lds_dwordx4 v195, s[98:99]
	s_add_i32 m0, s1, 0x8000
	s_nop 0
	global_load_lds_dwordx4 v198, s[98:99]
	s_add_i32 m0, s1, 0x9000
	s_nop 0
	global_load_lds_dwordx4 v199, s[98:99]
	s_add_i32 m0, s1, 0xa000
	s_nop 0
	global_load_lds_dwordx4 v194, s[100:101]
	s_add_i32 m0, s1, 0xb000
	s_nop 0
	global_load_lds_dwordx4 v195, s[100:101]
	s_add_u32 s98, s98, 0x40
	s_addc_u32 s99, s99, 0
	s_add_u32 s100, s100, 0x40
	s_addc_u32 s101, s101, 0
	ds_read_b128 v[132:135], v171
	ds_read_b128 v[136:139], v171 offset:2048
	ds_read_b128 v[140:143], v172
	ds_read_b128 v[144:147], v172 offset:2048
	ds_read_b128 v[148:151], v172 offset:4096
	ds_read_b128 v[152:155], v172 offset:6144
	ds_read_b128 v[174:177], v170
	ds_read_b128 v[178:181], v170 offset:2048
	ds_read_b128 v[182:185], v173
	ds_read_b128 v[186:189], v173 offset:2048
	ds_read_b128 v[190:193], v173 offset:4096
	ds_read_b128 v[218:221], v173 offset:6144
	s_waitcnt lgkmcnt(0)
	v_mfma_f32_32x32x16_bf16 v[116:131], v[132:135], v[140:143], v[116:131]
	v_mfma_f32_32x32x16_bf16 v[100:115], v[136:139], v[140:143], v[100:115]
	v_mfma_f32_32x32x16_bf16 v[84:99], v[132:135], v[144:147], v[84:99]
	v_mfma_f32_32x32x16_bf16 v[68:83], v[136:139], v[144:147], v[68:83]
	v_mfma_f32_32x32x16_bf16 v[52:67], v[132:135], v[148:151], v[52:67]
	v_mfma_f32_32x32x16_bf16 v[36:51], v[136:139], v[148:151], v[36:51]
	v_mfma_f32_32x32x16_bf16 v[20:35], v[132:135], v[152:155], v[20:35]
	v_mfma_f32_32x32x16_bf16 v[4:19], v[136:139], v[152:155], v[4:19]
	v_mfma_f32_32x32x16_bf16 v[116:131], v[174:177], v[182:185], v[116:131]
	v_mfma_f32_32x32x16_bf16 v[100:115], v[178:181], v[182:185], v[100:115]
	v_mfma_f32_32x32x16_bf16 v[84:99], v[174:177], v[186:189], v[84:99]
	v_mfma_f32_32x32x16_bf16 v[68:83], v[178:181], v[186:189], v[68:83]
	v_mfma_f32_32x32x16_bf16 v[52:67], v[174:177], v[190:193], v[52:67]
	v_mfma_f32_32x32x16_bf16 v[36:51], v[178:181], v[190:193], v[36:51]
	v_mfma_f32_32x32x16_bf16 v[20:35], v[174:177], v[218:221], v[20:35]
	v_mfma_f32_32x32x16_bf16 v[4:19], v[178:181], v[218:221], v[4:19]
	s_waitcnt vmcnt(0)
	s_waitcnt lgkmcnt(0)
	s_barrier
	ds_read_b128 v[132:135], v171 offset:24576
	ds_read_b128 v[136:139], v171 offset:26624
	ds_read_b128 v[140:143], v172 offset:24576
	ds_read_b128 v[144:147], v172 offset:26624
	ds_read_b128 v[148:151], v172 offset:28672
	ds_read_b128 v[152:155], v172 offset:30720
	ds_read_b128 v[174:177], v170 offset:24576
	ds_read_b128 v[178:181], v170 offset:26624
	ds_read_b128 v[182:185], v173 offset:24576
	ds_read_b128 v[186:189], v173 offset:26624
	ds_read_b128 v[190:193], v173 offset:28672
	ds_read_b128 v[218:221], v173 offset:30720
	s_waitcnt lgkmcnt(0)
	v_mfma_f32_32x32x16_bf16 v[116:131], v[132:135], v[140:143], v[116:131]
	v_mfma_f32_32x32x16_bf16 v[100:115], v[136:139], v[140:143], v[100:115]
	v_mfma_f32_32x32x16_bf16 v[84:99], v[132:135], v[144:147], v[84:99]
	v_mfma_f32_32x32x16_bf16 v[68:83], v[136:139], v[144:147], v[68:83]
	v_mfma_f32_32x32x16_bf16 v[52:67], v[132:135], v[148:151], v[52:67]
	v_mfma_f32_32x32x16_bf16 v[36:51], v[136:139], v[148:151], v[36:51]
	v_mfma_f32_32x32x16_bf16 v[20:35], v[132:135], v[152:155], v[20:35]
	v_mfma_f32_32x32x16_bf16 v[4:19], v[136:139], v[152:155], v[4:19]
	v_mfma_f32_32x32x16_bf16 v[116:131], v[174:177], v[182:185], v[116:131]
	v_mfma_f32_32x32x16_bf16 v[100:115], v[178:181], v[182:185], v[100:115]
	v_mfma_f32_32x32x16_bf16 v[84:99], v[174:177], v[186:189], v[84:99]
	v_mfma_f32_32x32x16_bf16 v[68:83], v[178:181], v[186:189], v[68:83]
	v_mfma_f32_32x32x16_bf16 v[52:67], v[174:177], v[190:193], v[52:67]
	v_mfma_f32_32x32x16_bf16 v[36:51], v[178:181], v[190:193], v[36:51]
	v_mfma_f32_32x32x16_bf16 v[20:35], v[174:177], v[218:221], v[20:35]
	v_mfma_f32_32x32x16_bf16 v[4:19], v[178:181], v[218:221], v[4:19]
	s_movk_i32 s0, 0xa00
	s_movk_i32 s11, 0x1400
	s_movk_i32 s14, 0xc00
	s_movk_i32 s16, 0xec00
	s_mov_b32 s17, -1
	s_movk_i32 s18, 0xec20
	s_mov_b32 s19, -1
	v_add_u32_e32 v148, s2, v168
	s_movk_i32 s20, 0xec40
	s_movk_i32 s2, 0x9e0
	s_mov_b32 s21, -1
	s_movk_i32 s24, 0xec60
	s_movk_i32 s4, 0x9d0
	s_mov_b64 s[22:23], 0x60
	s_mov_b32 s25, -1
	v_mov_b64_e32 v[134:135], s[6:7]
	v_mov_b64_e32 v[132:133], s[8:9]
	s_nop 10
	v_cvt_pk_bf16_f32 v116, v116, v117
	v_cvt_pk_bf16_f32 v117, v118, v119
	v_cvt_pk_bf16_f32 v118, v100, v101
	v_cvt_pk_bf16_f32 v119, v102, v103
	v_or_b32_e32 v140, s3, v169
	v_ashrrev_i32_e32 v141, 31, v140
	v_cmp_gt_i32_e32 vcc, s0, v140
	v_mad_i64_i32 v[142:143], s[0:1], v148, s14, v[132:133]
	v_cmp_gt_i32_e64 s[2:3], s2, v140
	v_cmp_gt_i32_e64 s[4:5], s4, v140
	s_nop 1
	v_cvt_pk_bf16_f32 v52, v52, v53
	v_cvt_pk_bf16_f32 v53, v54, v55
	s_nop 0
	v_cvt_pk_bf16_f32 v54, v36, v37
	v_cvt_pk_bf16_f32 v55, v38, v39
	v_mad_i64_i32 v[138:139], s[0:1], v148, s11, v[134:135]
	v_lshlrev_b64 v[136:137], 1, v[140:141]
	v_mov_b32_e32 v141, v3
	s_movk_i32 s0, 0x9f0
	v_cmp_gt_i32_e64 s[0:1], s0, v140
	v_cvt_pk_bf16_f32 v20, v20, v21
	v_cvt_pk_bf16_f32 v21, v22, v23
	s_nop 3
	v_cvt_pk_bf16_f32 v22, v4, v5
	v_cvt_pk_bf16_f32 v23, v6, v7
	v_lshl_add_u64 v[144:145], v[138:139], 0, v[136:137]
	v_lshlrev_b64 v[138:139], 1, v[140:141]
	v_lshl_add_u64 v[142:143], v[142:143], 0, v[138:139]
	v_lshl_add_u64 v[146:147], v[142:143], 0, s[16:17]
	v_cndmask_b32_e32 v147, v147, v145, vcc
	v_cndmask_b32_e32 v146, v146, v144, vcc
	v_lshl_add_u64 v[100:101], v[144:145], 0, 32
	v_lshl_add_u64 v[102:103], v[142:143], 0, s[18:19]
	global_store_dwordx4 v[146:147], v[116:119], off
	v_cvt_pk_bf16_f32 v84, v84, v85
	v_cvt_pk_bf16_f32 v85, v86, v87
; DI unsigned pack2(float a, float b) { f2_t v = {a, b}; return __builtin_bit_cast(unsigned, __builtin_convertvector(v, bf2_t)); }
;   template <int MF> DI void operator()(f32x16 (&acc)[MF][2], int mb, int nb, int l31, int h) const {
; #pragma unroll
;     for (int mi = 0; mi < MF; ++mi) {
;       const int row = mb + mi * 32 + l31;
; #pragma unroll
;       for (int g4 = 0; g4 < 4; ++g4) {
;         const int col0 = nb + 16 * g4 + 8 * h;
;         u16* dst = (col0 < 2560) ? zhg + (size_t)row * 2560 + col0 : zhy + (size_t)row * 1536 + (col0 - 2560);
;         *(u32x4*)dst = (u32x4){pack2(acc[mi][0][4 * g4], acc[mi][0][4 * g4 + 1]), pack2(acc[mi][0][4 * g4 + 2], acc[mi][0][4 * g4 + 3]),
;                                pack2(acc[mi][1][4 * g4], acc[mi][1][4 * g4 + 1]), pack2(acc[mi][1][4 * g4 + 2], acc[mi][1][4 * g4 + 3])};
;       }
;     }
;   }
	v_cndmask_b32_e64 v117, v103, v101, s[0:1]
	v_cndmask_b32_e64 v116, v102, v100, s[0:1]
	v_cvt_pk_bf16_f32 v100, v120, v121
	v_cvt_pk_bf16_f32 v101, v122, v123
	v_cvt_pk_bf16_f32 v102, v104, v105
	v_cvt_pk_bf16_f32 v103, v106, v107
	global_store_dwordx4 v[116:117], v[100:103], off
	v_cvt_pk_bf16_f32 v86, v68, v69
	v_cvt_pk_bf16_f32 v87, v70, v71
	v_lshl_add_u64 v[100:101], v[144:145], 0, 64
	v_lshl_add_u64 v[102:103], v[142:143], 0, s[20:21]
	v_cndmask_b32_e64 v105, v103, v101, s[2:3]
	v_cndmask_b32_e64 v104, v102, v100, s[2:3]
	v_cvt_pk_bf16_f32 v100, v124, v125
	v_cvt_pk_bf16_f32 v101, v126, v127
	v_cvt_pk_bf16_f32 v102, v108, v109
	v_cvt_pk_bf16_f32 v103, v110, v111
	global_store_dwordx4 v[104:105], v[100:103], off
	s_nop 1
	v_lshl_add_u64 v[100:101], v[144:145], 0, s[22:23]
	v_lshl_add_u64 v[102:103], v[142:143], 0, s[24:25]
	v_cndmask_b32_e64 v105, v103, v101, s[4:5]
	v_cndmask_b32_e64 v104, v102, v100, s[4:5]
	v_cvt_pk_bf16_f32 v100, v128, v129
	v_cvt_pk_bf16_f32 v101, v130, v131
	v_cvt_pk_bf16_f32 v102, v112, v113
	v_cvt_pk_bf16_f32 v103, v114, v115
	global_store_dwordx4 v[104:105], v[100:103], off
	s_nop 1
	v_or_b32_e32 v102, 32, v148
	v_mad_i64_i32 v[100:101], s[12:13], v102, s14, v[132:133]
	v_mad_i64_i32 v[102:103], s[12:13], v102, s11, v[134:135]
	v_lshl_add_u64 v[100:101], v[100:101], 0, v[138:139]
	v_lshl_add_u64 v[102:103], v[102:103], 0, v[136:137]
	v_lshl_add_u64 v[104:105], v[100:101], 0, s[16:17]
	v_cndmask_b32_e32 v105, v105, v103, vcc
	v_cndmask_b32_e32 v104, v104, v102, vcc
	v_lshl_add_u64 v[68:69], v[102:103], 0, 32
	v_lshl_add_u64 v[70:71], v[100:101], 0, s[18:19]
	global_store_dwordx4 v[104:105], v[84:87], off
	s_nop 1
	v_cndmask_b32_e64 v85, v71, v69, s[0:1]
	v_cndmask_b32_e64 v84, v70, v68, s[0:1]
	v_cvt_pk_bf16_f32 v68, v88, v89
	v_cvt_pk_bf16_f32 v69, v90, v91
	v_cvt_pk_bf16_f32 v70, v72, v73
	v_cvt_pk_bf16_f32 v71, v74, v75
	global_store_dwordx4 v[84:85], v[68:71], off
	s_nop 1
	v_lshl_add_u64 v[68:69], v[102:103], 0, 64
	v_lshl_add_u64 v[70:71], v[100:101], 0, s[20:21]
	v_cndmask_b32_e64 v73, v71, v69, s[2:3]
	v_cndmask_b32_e64 v72, v70, v68, s[2:3]
	v_cvt_pk_bf16_f32 v68, v92, v93
	v_cvt_pk_bf16_f32 v69, v94, v95
	v_cvt_pk_bf16_f32 v70, v76, v77
	v_cvt_pk_bf16_f32 v71, v78, v79
	global_store_dwordx4 v[72:73], v[68:71], off
	s_nop 1
	v_lshl_add_u64 v[68:69], v[102:103], 0, s[22:23]
	v_lshl_add_u64 v[70:71], v[100:101], 0, s[24:25]
	v_cndmask_b32_e64 v73, v71, v69, s[4:5]
	v_cndmask_b32_e64 v72, v70, v68, s[4:5]
	v_cvt_pk_bf16_f32 v68, v96, v97
	v_cvt_pk_bf16_f32 v69, v98, v99
	v_cvt_pk_bf16_f32 v70, v80, v81
	v_cvt_pk_bf16_f32 v71, v82, v83
	global_store_dwordx4 v[72:73], v[68:71], off
	s_nop 1
	v_or_b32_e32 v70, 64, v148
	v_mad_i64_i32 v[68:69], s[12:13], v70, s14, v[132:133]
	v_mad_i64_i32 v[70:71], s[12:13], v70, s11, v[134:135]
	v_lshl_add_u64 v[68:69], v[68:69], 0, v[138:139]
	v_lshl_add_u64 v[70:71], v[70:71], 0, v[136:137]
	v_lshl_add_u64 v[72:73], v[68:69], 0, s[16:17]
	v_cndmask_b32_e32 v73, v73, v71, vcc
	v_cndmask_b32_e32 v72, v72, v70, vcc
	v_lshl_add_u64 v[36:37], v[70:71], 0, 32
	v_lshl_add_u64 v[38:39], v[68:69], 0, s[18:19]
	global_store_dwordx4 v[72:73], v[52:55], off
	s_nop 1
	v_cndmask_b32_e64 v53, v39, v37, s[0:1]
	v_cndmask_b32_e64 v52, v38, v36, s[0:1]
	v_cvt_pk_bf16_f32 v36, v56, v57
	v_cvt_pk_bf16_f32 v37, v58, v59
	v_cvt_pk_bf16_f32 v38, v40, v41
	v_cvt_pk_bf16_f32 v39, v42, v43
	global_store_dwordx4 v[52:53], v[36:39], off
	s_nop 1
	v_lshl_add_u64 v[36:37], v[70:71], 0, 64
	v_lshl_add_u64 v[38:39], v[68:69], 0, s[20:21]
	v_cndmask_b32_e64 v41, v39, v37, s[2:3]
	v_cndmask_b32_e64 v40, v38, v36, s[2:3]
	v_cvt_pk_bf16_f32 v36, v60, v61
	v_cvt_pk_bf16_f32 v37, v62, v63
	v_cvt_pk_bf16_f32 v38, v44, v45
	v_cvt_pk_bf16_f32 v39, v46, v47
	global_store_dwordx4 v[40:41], v[36:39], off
	s_nop 1
	v_lshl_add_u64 v[36:37], v[70:71], 0, s[22:23]
	v_lshl_add_u64 v[38:39], v[68:69], 0, s[24:25]
	v_cndmask_b32_e64 v41, v39, v37, s[4:5]
	v_cndmask_b32_e64 v40, v38, v36, s[4:5]
	v_cvt_pk_bf16_f32 v36, v64, v65
	v_cvt_pk_bf16_f32 v37, v66, v67
	v_cvt_pk_bf16_f32 v38, v48, v49
	v_cvt_pk_bf16_f32 v39, v50, v51
	global_store_dwordx4 v[40:41], v[36:39], off
	s_nop 1
	v_or_b32_e32 v38, 0x60, v148
	v_mad_i64_i32 v[36:37], s[12:13], v38, s14, v[132:133]
	v_mad_i64_i32 v[38:39], s[12:13], v38, s11, v[134:135]
	v_lshl_add_u64 v[36:37], v[36:37], 0, v[138:139]
	v_lshl_add_u64 v[38:39], v[38:39], 0, v[136:137]
	v_lshl_add_u64 v[40:41], v[36:37], 0, s[16:17]
	v_cndmask_b32_e32 v41, v41, v39, vcc
	v_cndmask_b32_e32 v40, v40, v38, vcc
	v_lshl_add_u64 v[4:5], v[38:39], 0, 32
	v_lshl_add_u64 v[6:7], v[36:37], 0, s[18:19]
	global_store_dwordx4 v[40:41], v[20:23], off
	s_nop 1
	v_cndmask_b32_e64 v21, v7, v5, s[0:1]
	v_cndmask_b32_e64 v20, v6, v4, s[0:1]
	v_cvt_pk_bf16_f32 v4, v24, v25
	v_cvt_pk_bf16_f32 v5, v26, v27
	v_cvt_pk_bf16_f32 v6, v8, v9
	v_cvt_pk_bf16_f32 v7, v10, v11
	global_store_dwordx4 v[20:21], v[4:7], off
	v_readlane_b32 s0, v252, 40
	s_add_i32 s10, s10, s0
	v_lshl_add_u64 v[4:5], v[38:39], 0, 64
	v_lshl_add_u64 v[6:7], v[36:37], 0, s[20:21]
	v_cndmask_b32_e64 v9, v7, v5, s[2:3]
	v_cndmask_b32_e64 v8, v6, v4, s[2:3]
	v_cvt_pk_bf16_f32 v4, v28, v29
	v_cvt_pk_bf16_f32 v5, v30, v31
	v_cvt_pk_bf16_f32 v6, v12, v13
	v_cvt_pk_bf16_f32 v7, v14, v15
	global_store_dwordx4 v[8:9], v[4:7], off
	s_cmpk_gt_i32 s10, 0x10ff
	v_readlane_b32 s1, v252, 41
	v_lshl_add_u64 v[4:5], v[38:39], 0, s[22:23]
	v_lshl_add_u64 v[6:7], v[36:37], 0, s[24:25]
	v_cndmask_b32_e64 v9, v7, v5, s[4:5]
	v_cndmask_b32_e64 v8, v6, v4, s[4:5]
	v_cvt_pk_bf16_f32 v4, v32, v33
	v_cvt_pk_bf16_f32 v5, v34, v35
	v_cvt_pk_bf16_f32 v6, v16, v17
	v_cvt_pk_bf16_f32 v7, v18, v19
	global_store_dwordx4 v[8:9], v[4:7], off
	s_cbranch_scc0 .LBB0_953
